# v86 + the same gpost/gnext tail-row load de-serialisation in the fin-mix phase
# baseline (speedup 1.0000x reference)
.LBB0_303:
	v_mul_f32_e32 v44, v1, v1
	v_mul_f32_e32 v45, v5, v5
	v_fmac_f32_e32 v44, v0, v0
	v_fmac_f32_e32 v45, v4, v4
	v_fmac_f32_e32 v44, v2, v2
	v_fmac_f32_e32 v45, v6, v6
	v_fmac_f32_e32 v44, v3, v3
	v_fmac_f32_e32 v45, v7, v7
	v_add_f32_e32 v44, v44, v45
	v_mul_f32_e32 v45, v15, v15
	v_fmac_f32_e32 v45, v14, v14
	v_fmac_f32_e32 v45, v16, v16
	v_fmac_f32_e32 v45, v17, v17
	v_add_f32_e32 v44, v44, v45
	v_mul_f32_e32 v45, v19, v19
	v_fmac_f32_e32 v45, v18, v18
	v_fmac_f32_e32 v45, v20, v20
	v_fmac_f32_e32 v45, v21, v21
	v_add_f32_e32 v44, v44, v45
	ds_bpermute_b32 v45, v9, v44
	s_lshl_b64 s[14:15], s[68:69], 12
	s_add_u32 s68, s70, s14
	s_addc_u32 s69, s71, s15
	s_cmp_lt_i32 s12, 0x10200
	s_waitcnt lgkmcnt(0)
	v_add_f32_e32 v44, v44, v45
	ds_bpermute_b32 v45, v35, v44
	s_mov_b64 s[70:71], -1
	s_waitcnt lgkmcnt(0)
	v_add_f32_e32 v44, v44, v45
	ds_bpermute_b32 v45, v48, v44
	s_waitcnt lgkmcnt(0)
	v_add_f32_e32 v44, v44, v45
	ds_bpermute_b32 v45, v49, v44
	s_waitcnt lgkmcnt(0)
	v_add_f32_e32 v44, v44, v45
	ds_bpermute_b32 v45, v50, v44
	s_waitcnt lgkmcnt(0)
	v_add_f32_e32 v44, v44, v45
	ds_bpermute_b32 v45, v51, v44
	s_waitcnt lgkmcnt(0)
	v_add_f32_e32 v44, v44, v45
	v_fmamk_f32 v44, v44, 0x3a800000, v198
	v_cmp_gt_f32_e32 vcc, s31, v44
	v_mul_f32_e32 v45, 0x4f800000, v44
	s_nop 0
	v_cndmask_b32_e32 v44, v44, v45, vcc
	v_sqrt_f32_e32 v45, v44
	s_nop 0
	v_add_u32_e32 v46, -1, v45
	v_fma_f32 v47, -v46, v45, v44
	v_cmp_ge_f32_e64 s[44:45], 0, v47
	v_add_u32_e32 v47, 1, v45
	s_nop 0
	v_cndmask_b32_e64 v46, v45, v46, s[44:45]
	v_fma_f32 v45, -v47, v45, v44
	v_cmp_lt_f32_e64 s[44:45], 0, v45
	s_nop 1
	v_cndmask_b32_e64 v45, v46, v47, s[44:45]
	v_mul_f32_e32 v46, 0x37800000, v45
	v_cndmask_b32_e32 v45, v45, v46, vcc
	v_cmp_class_f32_e32 vcc, v44, v199
	s_cselect_b64 s[44:45], -1, 0
	s_nop 0
	v_cndmask_b32_e32 v44, v45, v44, vcc
	v_div_scale_f32 v45, s[14:15], v44, v44, 1.0
	v_rcp_f32_e32 v46, v45
	s_nop 0
	v_fma_f32 v47, -v45, v46, 1.0
	v_fmac_f32_e32 v46, v47, v46
	v_div_scale_f32 v47, vcc, 1.0, v44, 1.0
	v_mul_f32_e32 v52, v47, v46
	v_fma_f32 v53, -v45, v52, v47
	v_fmac_f32_e32 v52, v53, v46
	v_fma_f32 v45, -v45, v52, v47
	v_div_fmas_f32 v45, v45, v46, v52
	global_load_dwordx4 v[52:55], v[36:37], off
	global_load_dwordx4 v[170:173], v[36:37], off offset:1024
	global_load_dwordx4 v[174:177], v[36:37], off offset:2048
	global_load_dwordx4 v[178:181], v[36:37], off offset:3072
	v_div_fixup_f32 v44, v45, v44, 1.0
	v_pk_mul_f32 v[0:1], v[0:1], v[44:45] op_sel_hi:[1,0]
	v_pk_mul_f32 v[2:3], v[2:3], v[44:45] op_sel_hi:[1,0]
	s_and_b64 vcc, exec, s[62:63]
	s_waitcnt vmcnt(0)
	v_pk_fma_f32 v[2:3], v[54:55], v[2:3], v[32:33]
	v_pk_fma_f32 v[0:1], v[52:53], v[0:1], v[30:31]
	s_cbranch_vccz .LBB0_305
	v_cvt_pk_bf16_f32 v30, v0, v1
	v_cvt_pk_bf16_f32 v31, v2, v3
	global_store_dwordx2 v[42:43], v[30:31], off offset:-1536
	s_mov_b64 s[70:71], 0

.LBB0_308:
	s_nop 1
	v_mov_b32_e32 v30, v170
	v_mov_b32_e32 v31, v171
	v_mov_b32_e32 v32, v172
	v_mov_b32_e32 v33, v173
	v_mov_b32_e32 v45, v44
	v_mov_b32_e32 v52, v44
	v_mov_b32_e32 v53, v44
	v_pk_mul_f32 v[6:7], v[6:7], v[52:53]
	v_pk_mul_f32 v[4:5], v[4:5], v[44:45]
	s_and_b64 vcc, exec, s[42:43]
	s_mov_b64 s[68:69], -1
	v_pk_fma_f32 v[32:33], v[6:7], v[32:33], v[12:13]
	v_pk_fma_f32 v[30:31], v[4:5], v[30:31], v[10:11]
	s_cbranch_vccnz .LBB0_310
	v_cvt_pk_bf16_f32 v4, v30, v31
	v_cvt_pk_bf16_f32 v5, v32, v33
	s_mov_b64 s[68:69], 0
	global_store_dwordx2 v[42:43], v[4:5], off offset:-1024

.LBB0_313:
	s_nop 1
	v_mov_b32_e32 v4, v174
	v_mov_b32_e32 v5, v175
	v_mov_b32_e32 v6, v176
	v_mov_b32_e32 v7, v177
	v_mov_b32_e32 v10, v44
	v_mov_b32_e32 v11, v44
	v_pk_mul_f32 v[10:11], v[16:17], v[10:11]
	v_pk_mul_f32 v[12:13], v[14:15], v[44:45]
	s_mov_b64 s[68:69], -1
	s_and_b64 vcc, exec, s[42:43]
	v_pk_fma_f32 v[6:7], v[10:11], v[6:7], v[24:25]
	v_pk_fma_f32 v[4:5], v[12:13], v[4:5], v[22:23]
	s_cbranch_vccnz .LBB0_315
	v_cvt_pk_bf16_f32 v10, v4, v5
	v_cvt_pk_bf16_f32 v11, v6, v7
	s_mov_b64 s[68:69], 0
	global_store_dwordx2 v[42:43], v[10:11], off offset:-512

.LBB0_318:
	s_nop 1
	v_mov_b32_e32 v10, v178
	v_mov_b32_e32 v11, v179
	v_mov_b32_e32 v12, v180
	v_mov_b32_e32 v13, v181
	v_mov_b32_e32 v14, v44
	v_mov_b32_e32 v15, v44
	v_pk_mul_f32 v[16:17], v[18:19], v[44:45]
	v_pk_mul_f32 v[14:15], v[20:21], v[14:15]
	s_and_b64 vcc, exec, s[42:43]
	s_mov_b64 s[68:69], -1
	v_pk_fma_f32 v[12:13], v[14:15], v[12:13], v[28:29]
	v_pk_fma_f32 v[10:11], v[16:17], v[10:11], v[26:27]
	s_cbranch_vccnz .LBB0_320
	v_cvt_pk_bf16_f32 v14, v10, v11
	v_bfe_u32 v15, v12, 16, 1
	v_add3_u32 v15, v12, v15, s34
	v_bfe_u32 v16, v13, 16, 1
	v_lshrrev_b32_e32 v15, 16, v15
	v_add3_u32 v16, v13, v16, s34
	v_and_or_b32 v15, v16, s30, v15
	s_mov_b64 s[68:69], 0
	global_store_dwordx2 v[42:43], v[14:15], off

.LBB0_323:
	s_and_b64 vcc, exec, s[42:43]
	s_cbranch_vccnz .LBB0_260
	v_mul_f32_e32 v14, v1, v1
	v_mul_f32_e32 v15, v31, v31
	v_fmac_f32_e32 v14, v0, v0
	v_fmac_f32_e32 v15, v30, v30
	v_fmac_f32_e32 v14, v2, v2
	v_fmac_f32_e32 v15, v32, v32
	v_fmac_f32_e32 v14, v3, v3
	v_fmac_f32_e32 v15, v33, v33
	v_add_f32_e32 v14, v14, v15
	v_mul_f32_e32 v15, v5, v5
	v_fmac_f32_e32 v15, v4, v4
	v_fmac_f32_e32 v15, v6, v6
	v_fmac_f32_e32 v15, v7, v7
	v_add_f32_e32 v14, v14, v15
	v_mul_f32_e32 v15, v11, v11
	v_fmac_f32_e32 v15, v10, v10
	v_fmac_f32_e32 v15, v12, v12
	v_fmac_f32_e32 v15, v13, v13
	v_add_f32_e32 v14, v14, v15
	ds_bpermute_b32 v15, v9, v14
	v_mov_b32_e32 v21, v2
	v_mov_b32_e32 v2, v1
	v_mov_b32_e32 v20, v0
	s_waitcnt lgkmcnt(0)
	v_add_f32_e32 v14, v14, v15
	ds_bpermute_b32 v15, v35, v14
	s_waitcnt lgkmcnt(0)
	v_add_f32_e32 v14, v14, v15
	ds_bpermute_b32 v15, v48, v14
	s_waitcnt lgkmcnt(0)
	v_add_f32_e32 v14, v14, v15
	ds_bpermute_b32 v15, v49, v14
	s_waitcnt lgkmcnt(0)
	v_add_f32_e32 v14, v14, v15
	ds_bpermute_b32 v15, v50, v14
	s_waitcnt lgkmcnt(0)
	v_add_f32_e32 v14, v14, v15
	ds_bpermute_b32 v15, v51, v14
	s_waitcnt lgkmcnt(0)
	v_add_f32_e32 v14, v14, v15
	v_fmamk_f32 v14, v14, 0x3a800000, v198
	v_cmp_gt_f32_e32 vcc, s31, v14
	v_mul_f32_e32 v15, 0x4f800000, v14
	s_nop 0
	v_cndmask_b32_e32 v14, v14, v15, vcc
	v_sqrt_f32_e32 v15, v14
	s_nop 0
	v_add_u32_e32 v16, -1, v15
	v_fma_f32 v17, -v16, v15, v14
	v_cmp_ge_f32_e64 s[44:45], 0, v17
	v_add_u32_e32 v17, 1, v15
	s_nop 0
	v_cndmask_b32_e64 v16, v15, v16, s[44:45]
	v_fma_f32 v15, -v17, v15, v14
	v_cmp_lt_f32_e64 s[44:45], 0, v15
	s_nop 1
	v_cndmask_b32_e64 v15, v16, v17, s[44:45]
	v_mul_f32_e32 v16, 0x37800000, v15
	v_cndmask_b32_e32 v15, v15, v16, vcc
	v_cmp_class_f32_e32 vcc, v14, v199
	s_nop 1
	v_cndmask_b32_e32 v14, v15, v14, vcc
	v_div_scale_f32 v15, s[14:15], v14, v14, 1.0
	v_rcp_f32_e32 v16, v15
	s_nop 0
	v_fma_f32 v17, -v15, v16, 1.0
	v_fmac_f32_e32 v16, v17, v16
	v_div_scale_f32 v17, vcc, 1.0, v14, 1.0
	v_mul_f32_e32 v18, v17, v16
	v_fma_f32 v19, -v15, v18, v17
	v_fmac_f32_e32 v18, v19, v16
	v_fma_f32 v15, -v15, v18, v17
	v_div_fmas_f32 v15, v15, v16, v18
	global_load_dwordx4 v[16:19], v[38:39], off
	global_load_dwordx4 v[186:189], v[38:39], off offset:1024
	global_load_dwordx4 v[190:193], v[38:39], off offset:2048
	global_load_dwordx4 v[194:197], v[38:39], off offset:3072
	v_div_fixup_f32 v14, v15, v14, 1.0
	v_pk_mul_f32 v[0:1], v[2:3], v[14:15] op_sel_hi:[1,0]
	v_pk_mul_f32 v[20:21], v[20:21], v[14:15] op_sel_hi:[1,0]
	s_waitcnt vmcnt(0)
	v_mov_b32_e32 v23, v18
	v_mov_b32_e32 v18, v17
	v_mov_b32_e32 v22, v16
	v_pk_mul_f32 v[0:1], v[18:19], v[0:1]
	v_pk_mul_f32 v[20:21], v[22:23], v[20:21]
	v_and_b32_sdwa v15, v1, v200 dst_sel:DWORD dst_unused:UNUSED_PAD src0_sel:WORD_1 src1_sel:DWORD
	v_and_b32_sdwa v16, v0, v200 dst_sel:DWORD dst_unused:UNUSED_PAD src0_sel:WORD_1 src1_sel:DWORD
	v_and_b32_sdwa v2, v21, v200 dst_sel:DWORD dst_unused:UNUSED_PAD src0_sel:WORD_1 src1_sel:DWORD
	v_and_b32_sdwa v3, v20, v200 dst_sel:DWORD dst_unused:UNUSED_PAD src0_sel:WORD_1 src1_sel:DWORD
	v_add3_u32 v1, v1, v15, s34
	v_add3_u32 v0, v0, v16, s34
	v_add3_u32 v3, v20, v3, s34
	v_add3_u32 v2, v21, v2, s34
	v_and_b32_e32 v1, 0xffff0000, v1
	v_and_b32_e32 v0, 0xffff0000, v0
	v_add_co_u32_e32 v16, vcc, s88, v42
	v_or_b32_sdwa v1, v1, v2 dst_sel:DWORD dst_unused:UNUSED_PAD src0_sel:DWORD src1_sel:WORD_1
	v_or_b32_sdwa v0, v0, v3 dst_sel:DWORD dst_unused:UNUSED_PAD src0_sel:DWORD src1_sel:WORD_1
	v_addc_co_u32_e32 v17, vcc, -1, v43, vcc
	global_store_dwordx2 v[16:17], v[0:1], off offset:-1536
	s_nop 1
	v_mov_b32_e32 v0, v186
	v_mov_b32_e32 v1, v187
	v_mov_b32_e32 v2, v188
	v_mov_b32_e32 v3, v189
	v_mov_b32_e32 v18, v30
	v_mov_b32_e32 v19, v32
	v_pk_mul_f32 v[18:19], v[18:19], v[14:15] op_sel_hi:[1,0]
	v_mov_b32_e32 v32, v31
	v_mov_b32_e32 v20, v0
	v_mov_b32_e32 v21, v2
	v_pk_mul_f32 v[18:19], v[20:21], v[18:19]
	v_pk_mul_f32 v[20:21], v[32:33], v[14:15] op_sel_hi:[1,0]
	v_mov_b32_e32 v2, v1
	v_pk_mul_f32 v[0:1], v[2:3], v[20:21]
	v_and_b32_sdwa v3, v18, v200 dst_sel:DWORD dst_unused:UNUSED_PAD src0_sel:WORD_1 src1_sel:DWORD
	v_add3_u32 v3, v18, v3, s34
	v_and_b32_sdwa v15, v1, v200 dst_sel:DWORD dst_unused:UNUSED_PAD src0_sel:WORD_1 src1_sel:DWORD
	v_and_b32_sdwa v18, v0, v200 dst_sel:DWORD dst_unused:UNUSED_PAD src0_sel:WORD_1 src1_sel:DWORD
	v_and_b32_sdwa v2, v19, v200 dst_sel:DWORD dst_unused:UNUSED_PAD src0_sel:WORD_1 src1_sel:DWORD
	v_add3_u32 v1, v1, v15, s34
	v_add3_u32 v0, v0, v18, s34
	v_add3_u32 v2, v19, v2, s34
	v_and_b32_e32 v1, 0xffff0000, v1
	v_and_b32_e32 v0, 0xffff0000, v0
	v_or_b32_sdwa v1, v1, v2 dst_sel:DWORD dst_unused:UNUSED_PAD src0_sel:DWORD src1_sel:WORD_1
	v_or_b32_sdwa v0, v0, v3 dst_sel:DWORD dst_unused:UNUSED_PAD src0_sel:DWORD src1_sel:WORD_1
	global_store_dwordx2 v[16:17], v[0:1], off offset:-1024
	s_nop 1
	v_mov_b32_e32 v0, v190
	v_mov_b32_e32 v1, v191
	v_mov_b32_e32 v2, v192
	v_mov_b32_e32 v3, v193
	v_mov_b32_e32 v19, v6
	v_mov_b32_e32 v6, v5
	v_mov_b32_e32 v18, v4
	v_pk_mul_f32 v[4:5], v[6:7], v[14:15] op_sel_hi:[1,0]
	v_pk_mul_f32 v[18:19], v[18:19], v[14:15] op_sel_hi:[1,0]
	v_mov_b32_e32 v21, v2
	v_mov_b32_e32 v2, v1
	v_mov_b32_e32 v20, v0
	v_pk_mul_f32 v[0:1], v[2:3], v[4:5]
	v_pk_mul_f32 v[18:19], v[20:21], v[18:19]
	v_and_b32_sdwa v4, v1, v200 dst_sel:DWORD dst_unused:UNUSED_PAD src0_sel:WORD_1 src1_sel:DWORD
	v_and_b32_sdwa v5, v0, v200 dst_sel:DWORD dst_unused:UNUSED_PAD src0_sel:WORD_1 src1_sel:DWORD
	v_and_b32_sdwa v2, v19, v200 dst_sel:DWORD dst_unused:UNUSED_PAD src0_sel:WORD_1 src1_sel:DWORD
	v_and_b32_sdwa v3, v18, v200 dst_sel:DWORD dst_unused:UNUSED_PAD src0_sel:WORD_1 src1_sel:DWORD
	v_add3_u32 v1, v1, v4, s34
	v_add3_u32 v0, v0, v5, s34
	v_add3_u32 v3, v18, v3, s34
	v_add3_u32 v2, v19, v2, s34
	v_and_b32_e32 v1, 0xffff0000, v1
	v_and_b32_e32 v0, 0xffff0000, v0
	v_or_b32_sdwa v1, v1, v2 dst_sel:DWORD dst_unused:UNUSED_PAD src0_sel:DWORD src1_sel:WORD_1
	v_or_b32_sdwa v0, v0, v3 dst_sel:DWORD dst_unused:UNUSED_PAD src0_sel:DWORD src1_sel:WORD_1
	global_store_dwordx2 v[16:17], v[0:1], off offset:-512
	s_nop 1
	v_mov_b32_e32 v0, v194
	v_mov_b32_e32 v1, v195
	v_mov_b32_e32 v2, v196
	v_mov_b32_e32 v3, v197
	v_mov_b32_e32 v4, v10
	v_mov_b32_e32 v5, v12
	v_pk_mul_f32 v[4:5], v[4:5], v[14:15] op_sel_hi:[1,0]
	v_mov_b32_e32 v12, v11
	v_mov_b32_e32 v6, v0
	v_mov_b32_e32 v7, v2
	v_pk_mul_f32 v[4:5], v[4:5], v[6:7]
	v_pk_mul_f32 v[6:7], v[12:13], v[14:15] op_sel_hi:[1,0]
	v_mov_b32_e32 v2, v1
	v_pk_mul_f32 v[0:1], v[6:7], v[2:3]
	v_and_b32_sdwa v2, v5, v200 dst_sel:DWORD dst_unused:UNUSED_PAD src0_sel:WORD_1 src1_sel:DWORD
	v_and_b32_sdwa v3, v4, v200 dst_sel:DWORD dst_unused:UNUSED_PAD src0_sel:WORD_1 src1_sel:DWORD
	v_add3_u32 v3, v4, v3, s34
	v_add3_u32 v2, v5, v2, s34
	v_and_b32_sdwa v4, v1, v200 dst_sel:DWORD dst_unused:UNUSED_PAD src0_sel:WORD_1 src1_sel:DWORD
	v_and_b32_sdwa v5, v0, v200 dst_sel:DWORD dst_unused:UNUSED_PAD src0_sel:WORD_1 src1_sel:DWORD
	v_add3_u32 v1, v1, v4, s34
	v_add3_u32 v0, v0, v5, s34
	v_and_b32_e32 v1, 0xffff0000, v1
	v_and_b32_e32 v0, 0xffff0000, v0
	v_or_b32_sdwa v1, v1, v2 dst_sel:DWORD dst_unused:UNUSED_PAD src0_sel:DWORD src1_sel:WORD_1
	v_or_b32_sdwa v0, v0, v3 dst_sel:DWORD dst_unused:UNUSED_PAD src0_sel:DWORD src1_sel:WORD_1
	global_store_dwordx2 v[16:17], v[0:1], off
	s_branch .LBB0_260
